# GEMM_in main loop: all 8 MFMAs of k-substep 1 carried across the loop-back barrier (A0 fragment of the next stage read after the carried MFMAs that use its register)
# baseline (speedup 1.0000x reference)
; DI void gemm_tile(const Params& p, const GemmJob& j, int mt, int nt, char* smem) {
;     ...
;   const int t0 = mt * 256, n0 = nt * 128;
;   const int rl = lane >> 2, c8s = ((lane & 3) ^ ((lane >> 4) & 3)) * 8;
;   const int nk = j.K >> 5;
;   f32x16 acc[2][4];
; #pragma unroll
;   for (int a = 0; a < 2; ++a)
; #pragma unroll
;     for (int b = 0; b < 4; ++b)
; #pragma unroll
;       for (int i = 0; i < 16; ++i) acc[a][b][i] = 0.f;
;   auto glds = [&](int kt, int stage) {
;     char* sb = smem + stage * GSTAGE;
;     const unsigned ko = j.amode ? (unsigned)((kt >> 1) * j.lda + (kt & 1) * 32) : (unsigned)(kt * 32);
; #pragma unroll
;     for (int q = 0; q < 2; ++q) {
;       const int ch = q * 4 + wid;
;       const bf16_t* src = j.bblk ? j.Bt + ((size_t)kt * j.bblk + n0 + 16 * ch + rl) * 32 + c8s : j.Bt + (size_t)(n0 + 16 * ch + rl) * j.K + kt * 32 + c8s;
;       __builtin_amdgcn_global_load_lds((gptr_t)src, (lptr_t)(sb + ch * 1024), 16, 0, 0);
;     }
; #pragma unroll
;     for (int q = 0; q < 4; ++q) {
;       const int ch = q * 4 + wid;
;       const bf16_t* src = j.ablk ? j.A + ((size_t)kt * j.ablk + t0 + 16 * ch + rl) * 32 + c8s : j.A + a_rowoff(j, t0 + 16 * ch + rl) + ko + c8s;
;       __builtin_amdgcn_global_load_lds((gptr_t)src, (lptr_t)(sb + 8192 + ch * 1024), 16, 0, 0);
;     }
;   };
;   const int fr = (r >> 2) & 3; const int o0 = (h ^ fr) * 16;
;   __syncthreads();
;   glds(0, 0);
;   if (nk > 1) glds(1, 1);
;   int st = 0, st2 = 2;
.LBB0_102:
	v_lshl_add_u64 v[6:7], v[6:7], 0, v[0:1]
	s_add_i32 m0, s95, 0x6000
	v_readlane_b32 s12, v229, 29
	global_load_lds_dwordx4 v[6:7], off
	v_or_b32_e32 v7, s11, v3
	v_or_b32_e32 v6, s10, v2
	v_lshl_add_u64 v[10:11], v[6:7], 0, s[8:9]
	v_lshlrev_b64 v[10:11], 6, v[10:11]
	v_readlane_b32 s22, v229, 39
	v_readlane_b32 s23, v229, 40
	s_add_i32 m0, s94, 0x8000
	v_and_b32_e32 v144, 31, v145
	v_lshl_add_u64 v[10:11], s[22:23], 0, v[10:11]
	v_lshl_add_u64 v[10:11], v[10:11], 0, v[0:1]
	v_lshl_add_u64 v[10:11], v[10:11], 0, s[88:89]
	global_load_lds_dwordx4 v[10:11], off
	v_lshl_add_u64 v[10:11], v[6:7], 0, v[4:5]
	v_lshlrev_b64 v[10:11], 6, v[10:11]
	v_lshl_add_u64 v[10:11], s[22:23], 0, v[10:11]
	v_lshl_add_u64 v[10:11], v[10:11], 0, v[0:1]
	v_lshl_add_u64 v[10:11], v[10:11], 0, s[88:89]
	s_add_i32 m0, s95, 0x8000
	s_and_b32 s11, s72, 0x3ffff80
	global_load_lds_dwordx4 v[10:11], off
	v_lshl_add_u64 v[10:11], v[6:7], 0, s[62:63]
	v_lshlrev_b64 v[10:11], 6, v[10:11]
	v_lshl_add_u64 v[6:7], v[6:7], 0, s[66:67]
	v_lshl_add_u64 v[10:11], s[22:23], 0, v[10:11]
	v_lshlrev_b64 v[6:7], 6, v[6:7]
	v_lshl_add_u64 v[10:11], v[10:11], 0, v[0:1]
	v_lshl_add_u64 v[6:7], s[22:23], 0, v[6:7]
	v_lshl_add_u64 v[10:11], v[10:11], 0, s[88:89]
	s_add_i32 m0, s36, 0x8000
	v_lshl_add_u64 v[6:7], v[6:7], 0, v[0:1]
	global_load_lds_dwordx4 v[10:11], off
	v_lshl_add_u64 v[6:7], v[6:7], 0, s[88:89]
	s_add_i32 m0, s37, 0x8000
	s_and_b32 s38, s28, 3
	global_load_lds_dwordx4 v[6:7], off
	v_or_b32_e32 v7, s87, v3
	v_or_b32_e32 v6, s86, v2
	v_lshl_add_u64 v[130:131], v[6:7], 0, s[8:9]
	v_lshl_add_u64 v[132:133], v[6:7], 0, v[4:5]
	v_or_b32_e32 v6, s11, v144
	s_mul_i32 s11, s83, s75
	s_sub_i32 s11, s29, s11
	s_and_b32 s11, s11, 0xffffff80
	s_add_i32 s11, s8, s11
	v_lshlrev_b32_e32 v148, 6, v6
	v_add_u32_e32 v6, s11, v2
	s_lshl_b32 s11, s73, 5
	s_and_b32 s54, s81, 1
	v_lshlrev_b32_e32 v7, 6, v144
	s_add_i32 s11, s80, s11
	v_lshl_or_b32 v149, s54, 12, v7
	v_ashrrev_i32_e32 v7, 31, v6
	s_add_i32 s11, s11, s38
	v_lshlrev_b64 v[10:11], 11, v[6:7]
	v_add_u32_e32 v6, 64, v6
	s_lshl_b32 s11, s11, 8
	v_ashrrev_i32_e32 v7, 31, v6
	s_ashr_i32 s36, s11, 31
	v_and_b32_e32 v9, 63, v145
	v_lshlrev_b64 v[6:7], 11, v[6:7]
	v_or_b32_e32 v3, s36, v3
	v_or_b32_e32 v2, s11, v2
	v_lshrrev_b32_e32 v146, 5, v9
	v_lshrrev_b32_e32 v9, 2, v145
	v_lshl_add_u64 v[136:137], s[68:69], 0, v[6:7]
	v_lshl_add_u64 v[6:7], v[2:3], 0, s[8:9]
	v_lshlrev_b32_e32 v8, 4, v8
	v_lshl_add_u64 v[2:3], v[2:3], 0, v[4:5]
	v_bitop3_b32 v9, v146, v9, 3 bitop3:0x78
	v_lshlrev_b64 v[6:7], 6, v[6:7]
	v_and_b32_e32 v8, 48, v8
	v_lshlrev_b64 v[2:3], 6, v[2:3]
	v_readlane_b32 s8, v229, 8
	v_lshlrev_b32_e32 v147, 4, v9
	v_or_b32_e32 v6, v6, v8
	v_or_b32_e32 v2, v2, v8
	v_readlane_b32 s9, v229, 9
	v_mov_b32_e32 v114, 0
	s_mov_b32 s70, 2
	v_lshl_add_u64 v[134:135], s[68:69], 0, v[10:11]
	v_lshl_add_u64 v[138:139], s[22:23], 0, v[6:7]
	v_lshl_add_u64 v[140:141], s[8:9], 0, v[2:3]
	s_mov_b32 s11, 0
	s_mov_b64 s[8:9], 0
	s_mov_b32 s62, 0
	v_mov_b32_e32 v115, v114
	v_mov_b32_e32 v116, v114
	v_mov_b32_e32 v117, v114
	v_mov_b32_e32 v118, v114
	v_mov_b32_e32 v119, v114
	v_mov_b32_e32 v120, v114
	v_mov_b32_e32 v121, v114
	v_mov_b32_e32 v122, v114
	v_mov_b32_e32 v123, v114
	v_mov_b32_e32 v124, v114
	v_mov_b32_e32 v125, v114
	v_mov_b32_e32 v126, v114
	v_mov_b32_e32 v127, v114
	v_mov_b32_e32 v128, v114
	v_mov_b32_e32 v129, v114
	v_mov_b32_e32 v82, v114
	v_mov_b32_e32 v83, v114
	v_mov_b32_e32 v84, v114
	v_mov_b32_e32 v85, v114
	v_mov_b32_e32 v86, v114
	v_mov_b32_e32 v87, v114
	v_mov_b32_e32 v88, v114
	v_mov_b32_e32 v89, v114
	v_mov_b32_e32 v90, v114
	v_mov_b32_e32 v91, v114
	v_mov_b32_e32 v92, v114
	v_mov_b32_e32 v93, v114
	v_mov_b32_e32 v94, v114
	v_mov_b32_e32 v95, v114
	v_mov_b32_e32 v96, v114
	v_mov_b32_e32 v97, v114
	v_mov_b32_e32 v50, v114
	v_mov_b32_e32 v51, v114
	v_mov_b32_e32 v52, v114
	v_mov_b32_e32 v53, v114
	v_mov_b32_e32 v54, v114
	v_mov_b32_e32 v55, v114
	v_mov_b32_e32 v56, v114
	v_mov_b32_e32 v57, v114
	v_mov_b32_e32 v58, v114
	v_mov_b32_e32 v59, v114
	v_mov_b32_e32 v60, v114
	v_mov_b32_e32 v61, v114
	v_mov_b32_e32 v62, v114
	v_mov_b32_e32 v63, v114
	v_mov_b32_e32 v64, v114
	v_mov_b32_e32 v65, v114
	v_mov_b32_e32 v18, v114
	v_mov_b32_e32 v19, v114
	v_mov_b32_e32 v20, v114
	v_mov_b32_e32 v21, v114
	v_mov_b32_e32 v22, v114
	v_mov_b32_e32 v23, v114
	v_mov_b32_e32 v24, v114
	v_mov_b32_e32 v25, v114
	v_mov_b32_e32 v26, v114
	v_mov_b32_e32 v27, v114
	v_mov_b32_e32 v28, v114
	v_mov_b32_e32 v29, v114
	v_mov_b32_e32 v30, v114
	v_mov_b32_e32 v31, v114
	v_mov_b32_e32 v32, v114
	v_mov_b32_e32 v33, v114
	v_mov_b32_e32 v98, v114
	v_mov_b32_e32 v99, v114
	v_mov_b32_e32 v100, v114
	v_mov_b32_e32 v101, v114
	v_mov_b32_e32 v102, v114
	v_mov_b32_e32 v103, v114
	v_mov_b32_e32 v104, v114
	v_mov_b32_e32 v105, v114
	v_mov_b32_e32 v106, v114
	v_mov_b32_e32 v107, v114
	v_mov_b32_e32 v108, v114
	v_mov_b32_e32 v109, v114
	v_mov_b32_e32 v110, v114
	v_mov_b32_e32 v111, v114
	v_mov_b32_e32 v112, v114
	v_mov_b32_e32 v113, v114
	v_mov_b32_e32 v66, v114
	v_mov_b32_e32 v67, v114
	v_mov_b32_e32 v68, v114
	v_mov_b32_e32 v69, v114
	v_mov_b32_e32 v70, v114
	v_mov_b32_e32 v71, v114
	v_mov_b32_e32 v72, v114
	v_mov_b32_e32 v73, v114
	v_mov_b32_e32 v74, v114
	v_mov_b32_e32 v75, v114
	v_mov_b32_e32 v76, v114
; DI f32x16 mfma32(bf16x8 a, bf16x8 b, f32x16 c) { return __builtin_amdgcn_mfma_f32_32x32x16_bf16(a, b, c, 0, 0, 0); }
; #define RAW_BARRIER() do { asm volatile("s_waitcnt lgkmcnt(0)" ::: "memory"); __builtin_amdgcn_s_barrier(); } while (0)
; DI void gemm_tile(const Params& p, const GemmJob& j, int mt, int nt, char* smem) {
;     ...
;   f32x16 acc[2][4];
; #pragma unroll
;   for (int a = 0; a < 2; ++a)
; #pragma unroll
;     for (int b = 0; b < 4; ++b)
; #pragma unroll
;       for (int i = 0; i < 16; ++i) acc[a][b][i] = 0.f;
;   auto glds = [&](int kt, int stage) {
;     char* sb = smem + stage * GSTAGE;
;     const unsigned ko = j.amode ? (unsigned)((kt >> 1) * j.lda + (kt & 1) * 32) : (unsigned)(kt * 32);
; #pragma unroll
;     for (int q = 0; q < 2; ++q) {
;       const int ch = q * 4 + wid;
;       const bf16_t* src = j.bblk ? j.Bt + ((size_t)kt * j.bblk + n0 + 16 * ch + rl) * 32 + c8s : j.Bt + (size_t)(n0 + 16 * ch + rl) * j.K + kt * 32 + c8s;
;       __builtin_amdgcn_global_load_lds((gptr_t)src, (lptr_t)(sb + ch * 1024), 16, 0, 0);
;     }
; #pragma unroll
;     for (int q = 0; q < 4; ++q) {
;       const int ch = q * 4 + wid;
;       const bf16_t* src = j.ablk ? j.A + ((size_t)kt * j.ablk + t0 + 16 * ch + rl) * 32 + c8s : j.A + a_rowoff(j, t0 + 16 * ch + rl) + ko + c8s;
;       __builtin_amdgcn_global_load_lds((gptr_t)src, (lptr_t)(sb + 8192 + ch * 1024), 16, 0, 0);
;     }
;   };
;   const int fr = (r >> 2) & 3; const int o0 = (h ^ fr) * 16;
;   __syncthreads();
;   glds(0, 0);
;   if (nk > 1) glds(1, 1);
;   int st = 0, st2 = 2;
;   for (int kt = 0; kt < nk; ++kt) {
;     if (kt + 1 < nk) asm volatile("s_waitcnt vmcnt(6)" ::: "memory"); else asm volatile("s_waitcnt vmcnt(0)" ::: "memory");
;     RAW_BARRIER();
;     if (kt + 2 < nk) glds(kt + 2, st2);
;     const char* sb = smem + st * GSTAGE;
; #pragma unroll
;     for (int ks = 0; ks < 2; ++ks) {
;       const int off = ks ? (o0 ^ 32) : o0;
;       bf16x8 wf[2], xf[4];
; #pragma unroll
;       for (int a = 0; a < 2; ++a) wf[a] = *(const bf16x8*)(sb + (64 * wn + 32 * a + r) * 64 + off);
; #pragma unroll
;       for (int b = 0; b < 4; ++b) xf[b] = *(const bf16x8*)(sb + 8192 + (128 * wt + 32 * b + r) * 64 + off);
; #pragma unroll
;       for (int a = 0; a < 2; ++a)
; #pragma unroll
;         for (int b = 0; b < 4; ++b) acc[a][b] = mfma32(wf[a], xf[b], acc[a][b]);
	v_mov_b32_e32 v77, v114
	v_mov_b32_e32 v78, v114
	v_mov_b32_e32 v79, v114
	v_mov_b32_e32 v80, v114
	v_mov_b32_e32 v81, v114
	v_mov_b32_e32 v34, v114
	v_mov_b32_e32 v35, v114
	v_mov_b32_e32 v36, v114
	v_mov_b32_e32 v37, v114
	v_mov_b32_e32 v38, v114
	v_mov_b32_e32 v39, v114
	v_mov_b32_e32 v40, v114
	v_mov_b32_e32 v41, v114
	v_mov_b32_e32 v42, v114
	v_mov_b32_e32 v43, v114
	v_mov_b32_e32 v44, v114
	v_mov_b32_e32 v45, v114
	v_mov_b32_e32 v46, v114
	v_mov_b32_e32 v47, v114
	v_mov_b32_e32 v48, v114
	v_mov_b32_e32 v49, v114
	v_mov_b32_e32 v2, v114
	v_mov_b32_e32 v3, v114
	v_mov_b32_e32 v4, v114
	v_mov_b32_e32 v5, v114
	v_mov_b32_e32 v6, v114
	v_mov_b32_e32 v7, v114
	v_mov_b32_e32 v8, v114
	v_mov_b32_e32 v9, v114
	v_mov_b32_e32 v10, v114
	v_mov_b32_e32 v11, v114
	v_mov_b32_e32 v12, v114
	v_mov_b32_e32 v13, v114
	v_mov_b32_e32 v14, v114
	v_mov_b32_e32 v15, v114
	v_mov_b32_e32 v16, v114
	v_mov_b32_e32 v17, v114
	v_xor_b32_e32 v150, 32, v147
	v_readlane_b32 s13, v229, 30
	v_readlane_b32 s14, v229, 31
	v_readlane_b32 s15, v229, 32
	v_readlane_b32 s16, v229, 33
	v_readlane_b32 s17, v229, 34
	v_readlane_b32 s18, v229, 35
	v_readlane_b32 s19, v229, 36
	v_readlane_b32 s20, v229, 37
	v_readlane_b32 s21, v229, 38
	v_readlane_b32 s24, v229, 41
	v_readlane_b32 s25, v229, 42
	v_readlane_b32 s26, v229, 43
	v_readlane_b32 s27, v229, 44
	v_mov_b32_e32 v152, 0
	v_mov_b32_e32 v153, 0
	v_mov_b32_e32 v154, 0
	v_mov_b32_e32 v155, 0
	v_mov_b32_e32 v236, 0
	v_mov_b32_e32 v237, 0
	v_mov_b32_e32 v238, 0
	v_mov_b32_e32 v239, 0
	v_mov_b32_e32 v240, 0
	v_mov_b32_e32 v241, 0
	v_mov_b32_e32 v242, 0
	v_mov_b32_e32 v243, 0
	v_mov_b32_e32 v244, 0
	v_mov_b32_e32 v245, 0
	v_mov_b32_e32 v246, 0
	v_mov_b32_e32 v247, 0
	v_mov_b32_e32 v248, 0
	v_mov_b32_e32 v249, 0
	v_mov_b32_e32 v250, 0
	v_mov_b32_e32 v251, 0
	v_mov_b32_e32 v252, 0
	v_mov_b32_e32 v253, 0
	v_mov_b32_e32 v254, 0
	v_mov_b32_e32 v255, 0
	s_branch .LBB0_104
.LBB0_103:
	s_add_i32 s37, s63, s33
	v_lshl_add_u64 v[232:233], v[232:233], 0, v[0:1]
	s_mov_b32 m0, s37
	v_lshl_add_u64 v[134:135], v[134:135], 0, 64
	global_load_lds_dwordx4 v[232:233], off
	v_mfma_f32_32x32x16_bf16 v[82:97], v[152:155], v[244:247], v[82:97]
	v_lshl_add_u64 v[232:233], v[138:139], 0, s[8:9]
	v_lshl_add_u64 v[234:235], v[232:233], 0, s[92:93]
	s_add_i32 m0, s36, 0x2000
	s_add_i32 s36, s63, s55
	global_load_lds_dwordx4 v[234:235], off
	v_mfma_f32_32x32x16_bf16 v[50:65], v[152:155], v[248:251], v[50:65]
	v_lshl_add_u64 v[234:235], v[140:141], 0, s[8:9]
	s_add_i32 m0, s37, 0x2000
	v_lshl_add_u64 v[136:137], v[136:137], 0, 64
	global_load_lds_dwordx4 v[234:235], off
	v_mfma_f32_32x32x16_bf16 v[18:33], v[152:155], v[252:255], v[18:33]
	ds_read_b128 v[152:155], v143
	v_lshl_add_u64 v[234:235], v[232:233], 0, s[84:85]
	s_add_i32 m0, s36, 0x2000
	s_add_i32 s36, s63, s58
	global_load_lds_dwordx4 v[234:235], off
	v_mfma_f32_32x32x16_bf16 v[98:113], v[236:239], v[240:243], v[98:113]
	v_lshl_add_u64 v[232:233], v[232:233], 0, s[52:53]
	s_add_i32 m0, s36, 0x2000
	s_nop 0
	global_load_lds_dwordx4 v[232:233], off
	v_mfma_f32_32x32x16_bf16 v[66:81], v[236:239], v[244:247], v[66:81]
	v_mfma_f32_32x32x16_bf16 v[34:49], v[236:239], v[248:251], v[34:49]
	v_mfma_f32_32x32x16_bf16 v[2:17], v[236:239], v[252:255], v[2:17]
	v_add_u32_e32 v234, s100, v150
	v_add_u32_e32 v235, v234, v149
	v_add_u32_e32 v234, v234, v148
	s_waitcnt lgkmcnt(0)
	v_mfma_f32_32x32x16_bf16 v[114:129], v[152:155], v[156:159], v[114:129]
	ds_read_b128 v[236:239], v143 offset:2048
	s_add_i32 s36, s11, 1
	s_cmp_lg_u32 s11, 2
	s_cselect_b32 s11, s36, 0
	s_add_i32 s36, s70, 1
	s_cmp_lg_u32 s70, 2
	s_cselect_b32 s70, s36, 0
	v_mfma_f32_32x32x16_bf16 v[82:97], v[152:155], v[160:163], v[82:97]
	ds_read_b128 v[240:243], v234 offset:8192
	s_add_u32 s8, s8, 0x200000
	s_addc_u32 s9, s9, 0
	s_add_i32 s62, s62, 1
	s_cmp_eq_u32 s8, 0x3c00000
	v_mfma_f32_32x32x16_bf16 v[50:65], v[152:155], v[180:183], v[50:65]
	ds_read_b128 v[244:247], v234 offset:10240
	v_mfma_f32_32x32x16_bf16 v[18:33], v[152:155], v[184:187], v[18:33]
	ds_read_b128 v[248:251], v234 offset:12288
	s_waitcnt lgkmcnt(3)
	v_mfma_f32_32x32x16_bf16 v[98:113], v[236:239], v[156:159], v[98:113]
	ds_read_b128 v[252:255], v234 offset:14336
	v_mfma_f32_32x32x16_bf16 v[66:81], v[236:239], v[160:163], v[66:81]
	ds_read_b128 v[152:155], v235
	v_mfma_f32_32x32x16_bf16 v[34:49], v[236:239], v[180:183], v[34:49]
	v_mfma_f32_32x32x16_bf16 v[2:17], v[236:239], v[184:187], v[2:17]
	ds_read_b128 v[236:239], v235 offset:2048
	s_cbranch_scc1 .LBB0_108
.LBB0_104:
	s_waitcnt vmcnt(6)
	s_waitcnt lgkmcnt(0)
	s_add_i32 s37, s62, 2
	s_and_b64 vcc, exec, s[6:7]
	s_mul_i32 s38, s37, s3
	v_mov_b64_e32 v[232:233], v[134:135]
	s_mul_i32 s100, s11, 0x6000
	v_add_u32_e32 v142, s100, v147
	v_add_u32_e32 v143, v142, v149
	v_add_u32_e32 v142, v142, v148
	s_barrier
	v_mfma_f32_32x32x16_bf16 v[114:129], v[152:155], v[240:243], v[114:129]
	ds_read_b128 v[156:159], v142 offset:8192
	ds_read_b128 v[160:163], v142 offset:10240
	ds_read_b128 v[180:183], v142 offset:12288
	ds_read_b128 v[184:187], v142 offset:14336
	s_cbranch_vccnz .LBB0_106
	v_mov_b32_e32 v232, s2
	v_mad_u64_u32 v[232:233], s[40:41], s37, v232, v[130:131]
	v_add_u32_e32 v233, s38, v233
	v_lshlrev_b64 v[232:233], 6, v[232:233]
	v_lshl_add_u64 v[232:233], s[4:5], 0, v[232:233]

; DI f32x16 mfma32(bf16x8 a, bf16x8 b, f32x16 c) { return __builtin_amdgcn_mfma_f32_32x32x16_bf16(a, b, c, 0, 0, 0); }
; #define RAW_BARRIER() do { asm volatile("s_waitcnt lgkmcnt(0)" ::: "memory"); __builtin_amdgcn_s_barrier(); } while (0)
; DI void gemm_tile(const Params& p, const GemmJob& j, int mt, int nt, char* smem) {
;     ...
;   for (int kt = 0; kt < nk; ++kt) {
;     if (kt + 1 < nk) asm volatile("s_waitcnt vmcnt(6)" ::: "memory"); else asm volatile("s_waitcnt vmcnt(0)" ::: "memory");
;     RAW_BARRIER();
;     if (kt + 2 < nk) glds(kt + 2, st2);
;     const char* sb = smem + st * GSTAGE;
; #pragma unroll
;     for (int ks = 0; ks < 2; ++ks) {
;       const int off = ks ? (o0 ^ 32) : o0;
;       bf16x8 wf[2], xf[4];
; #pragma unroll
;       for (int a = 0; a < 2; ++a) wf[a] = *(const bf16x8*)(sb + (64 * wn + 32 * a + r) * 64 + off);
; #pragma unroll
;       for (int b = 0; b < 4; ++b) xf[b] = *(const bf16x8*)(sb + 8192 + (128 * wt + 32 * b + r) * 64 + off);
; #pragma unroll
;       for (int a = 0; a < 2; ++a)
; #pragma unroll
;         for (int b = 0; b < 4; ++b) acc[a][b] = mfma32(wf[a], xf[b], acc[a][b]);
;     }
;     st = (st == 2) ? 0 : st + 1; st2 = (st2 == 2) ? 0 : st2 + 1;
;   }
;   __syncthreads();
;   if (j.epi == E_SEG) {
;     const float* sp = p.ssqp + (size_t)(t0 + tid) * 8;
;     const f32x4 s0 = *(const f32x4*)sp, s1 = *(const f32x4*)(sp + 4);
;     rstd_s[tid] = rsqrtf(((s0[0] + s0[1]) + (s0[2] + s0[3]) + (s1[0] + s1[1]) + (s1[2] + s1[3])) * (1.f / 1024.f) + 1e-6f);
;     __syncthreads();
;   }
;   const int cb = n0 + 64 * wn;
;   if (j.epi == E_SEG) {
;     const Seg* sg = p.segs[j.layer]; const int nsg = p.nseg[j.layer];
;     {
;       int si = 0;
;       for (int q = 1; q < nsg; ++q) if (cb >= sg[q].nb) si = q;
.LBB0_108:
	s_waitcnt lgkmcnt(0)
	v_mfma_f32_32x32x16_bf16 v[114:129], v[152:155], v[240:243], v[114:129]
	v_mfma_f32_32x32x16_bf16 v[82:97], v[152:155], v[244:247], v[82:97]
	v_mfma_f32_32x32x16_bf16 v[50:65], v[152:155], v[248:251], v[50:65]
	v_mfma_f32_32x32x16_bf16 v[18:33], v[152:155], v[252:255], v[18:33]
	v_mfma_f32_32x32x16_bf16 v[98:113], v[236:239], v[240:243], v[98:113]
	v_mfma_f32_32x32x16_bf16 v[66:81], v[236:239], v[244:247], v[66:81]
	v_mfma_f32_32x32x16_bf16 v[34:49], v[236:239], v[248:251], v[34:49]
	v_mfma_f32_32x32x16_bf16 v[2:17], v[236:239], v[252:255], v[2:17]
	v_readlane_b32 s100, v229, 35
	v_readlane_b32 s101, v229, 36
	v_add_u32_e32 v244, s10, v145
	v_ashrrev_i32_e32 v245, 31, v244
	v_lshlrev_b64 v[244:245], 5, v[244:245]
	s_nop 0
	v_lshl_add_u64 v[244:245], s[100:101], 0, v[244:245]
	global_load_dwordx4 v[236:239], v[244:245], off offset:16
	global_load_dwordx4 v[240:243], v[244:245], off
	s_mul_i32 s6, s11, 0x6000
	s_add_i32 s7, s6, 0
	v_add_u32_e32 v0, s7, v147
	s_waitcnt vmcnt(8)
	v_add_u32_e32 v134, v0, v149
	v_add_u32_e32 v0, v0, v148
	s_waitcnt lgkmcnt(0)
	s_barrier
	ds_read_b128 v[130:133], v134
	ds_read_b128 v[134:137], v134 offset:2048
	ds_read_b128 v[138:141], v0 offset:8192
	ds_read_b128 v[152:155], v0 offset:10240
	ds_read_b128 v[156:159], v0 offset:12288
	ds_read_b128 v[160:163], v0 offset:14336
	s_waitcnt lgkmcnt(0)
	v_mfma_f32_32x32x16_bf16 v[114:129], v[130:133], v[138:141], v[114:129]
	v_add_u32_e32 v0, s7, v150
	s_addk_i32 s6, 0x6000
	s_cmp_lg_u32 s11, 2
	s_cselect_b32 s6, s6, 0
	s_add_i32 s6, s6, 0
	v_readlane_b32 s12, v229, 29
	v_readlane_b32 s18, v229, 35
	v_mfma_f32_32x32x16_bf16 v[82:97], v[130:133], v[152:155], v[82:97]
	v_readlane_b32 s19, v229, 36
	v_readlane_b32 s13, v229, 30
	v_readlane_b32 s14, v229, 31
	v_readlane_b32 s15, v229, 32
	v_readlane_b32 s16, v229, 33
	v_readlane_b32 s17, v229, 34
	v_readlane_b32 s20, v229, 37
	v_mfma_f32_32x32x16_bf16 v[50:65], v[130:133], v[156:159], v[50:65]
	v_readlane_b32 s21, v229, 38
	v_readlane_b32 s22, v229, 39
	v_readlane_b32 s23, v229, 40
	v_readlane_b32 s24, v229, 41
	v_readlane_b32 s25, v229, 42
	v_readlane_b32 s26, v229, 43
	v_readlane_b32 s27, v229, 44
	v_mfma_f32_32x32x16_bf16 v[18:33], v[130:133], v[160:163], v[18:33]
	v_mfma_f32_32x32x16_bf16 v[98:113], v[134:137], v[138:141], v[98:113]
	v_mfma_f32_32x32x16_bf16 v[66:81], v[134:137], v[152:155], v[66:81]
	v_mfma_f32_32x32x16_bf16 v[34:49], v[134:137], v[156:159], v[34:49]
	v_mfma_f32_32x32x16_bf16 v[2:17], v[134:137], v[160:163], v[2:17]
	v_add_u32_e32 v134, v0, v149
	v_add_u32_e32 v0, v0, v148
	ds_read_b128 v[130:133], v134
	ds_read_b128 v[134:137], v134 offset:2048
	ds_read_b128 v[138:141], v0 offset:8192
	ds_read_b128 v[152:155], v0 offset:10240
	ds_read_b128 v[156:159], v0 offset:12288
	ds_read_b128 v[160:163], v0 offset:14336
	v_add_u32_e32 v0, s6, v147
	s_waitcnt vmcnt(0)
	s_waitcnt lgkmcnt(0)
	s_waitcnt lgkmcnt(0)
	v_mfma_f32_32x32x16_bf16 v[114:129], v[130:133], v[138:141], v[114:129]
	s_barrier
	v_mfma_f32_32x32x16_bf16 v[82:97], v[130:133], v[152:155], v[82:97]
	v_mfma_f32_32x32x16_bf16 v[50:65], v[130:133], v[156:159], v[50:65]
	v_mfma_f32_32x32x16_bf16 v[18:33], v[130:133], v[160:163], v[18:33]
	v_mfma_f32_32x32x16_bf16 v[98:113], v[134:137], v[138:141], v[98:113]
	v_mfma_f32_32x32x16_bf16 v[66:81], v[134:137], v[152:155], v[66:81]
	v_mfma_f32_32x32x16_bf16 v[34:49], v[134:137], v[156:159], v[34:49]
	v_mfma_f32_32x32x16_bf16 v[2:17], v[134:137], v[160:163], v[2:17]
	v_add_u32_e32 v134, v0, v149
	v_add_u32_e32 v0, v0, v148
	ds_read_b128 v[130:133], v134
	ds_read_b128 v[134:137], v134 offset:2048
	ds_read_b128 v[138:141], v0 offset:8192
	ds_read_b128 v[152:155], v0 offset:10240
	ds_read_b128 v[156:159], v0 offset:12288
	ds_read_b128 v[160:163], v0 offset:14336
	v_add_u32_e32 v0, s6, v150
	s_mov_b32 s6, 0x800000
	s_waitcnt lgkmcnt(0)
	v_mfma_f32_32x32x16_bf16 v[114:129], v[130:133], v[138:141], v[114:129]
	v_mfma_f32_32x32x16_bf16 v[82:97], v[130:133], v[152:155], v[82:97]
	v_mfma_f32_32x32x16_bf16 v[50:65], v[130:133], v[156:159], v[50:65]
	v_mfma_f32_32x32x16_bf16 v[18:33], v[130:133], v[160:163], v[18:33]
	v_mfma_f32_32x32x16_bf16 v[98:113], v[134:137], v[138:141], v[98:113]
	v_mfma_f32_32x32x16_bf16 v[66:81], v[134:137], v[152:155], v[66:81]
	v_mfma_f32_32x32x16_bf16 v[34:49], v[134:137], v[156:159], v[34:49]
	v_mfma_f32_32x32x16_bf16 v[2:17], v[134:137], v[160:163], v[2:17]
	v_add_u32_e32 v134, v0, v149
	v_add_u32_e32 v0, v0, v148
	ds_read_b128 v[130:133], v134
	ds_read_b128 v[134:137], v134 offset:2048
	ds_read_b128 v[138:141], v0 offset:8192
	ds_read_b128 v[148:151], v0 offset:10240
	ds_read_b128 v[152:155], v0 offset:12288
	ds_read_b128 v[156:159], v0 offset:14336
	s_waitcnt vmcnt(0) lgkmcnt(0)
	s_barrier
	v_mfma_f32_32x32x16_bf16 v[114:129], v[130:133], v[138:141], v[114:129]
	v_mfma_f32_32x32x16_bf16 v[82:97], v[130:133], v[148:151], v[82:97]
	v_mfma_f32_32x32x16_bf16 v[50:65], v[130:133], v[152:155], v[50:65]
	v_mfma_f32_32x32x16_bf16 v[18:33], v[130:133], v[156:159], v[18:33]
	v_add_u32_e32 v130, s10, v145
	v_ashrrev_i32_e32 v131, 31, v130
	v_lshlrev_b64 v[130:131], 5, v[130:131]
	v_mfma_f32_32x32x16_bf16 v[98:113], v[134:137], v[138:141], v[98:113]
	v_mfma_f32_32x32x16_bf16 v[66:81], v[134:137], v[148:151], v[66:81]
	v_mfma_f32_32x32x16_bf16 v[34:49], v[134:137], v[152:155], v[34:49]
	v_mfma_f32_32x32x16_bf16 v[2:17], v[134:137], v[156:159], v[2:17]
	v_lshl_add_u64 v[134:135], s[18:19], 0, v[130:131]
	s_waitcnt vmcnt(0)
	v_mov_b32_e32 v130, v236
	v_mov_b32_e32 v131, v237
	v_mov_b32_e32 v132, v238
	v_mov_b32_e32 v133, v239
	v_mov_b32_e32 v134, v240
	v_mov_b32_e32 v135, v241
	v_mov_b32_e32 v136, v242
	v_mov_b32_e32 v137, v243
	v_mov_b32_e32 v138, v135
	v_mov_b32_e32 v139, v136
	v_mov_b32_e32 v135, v137
	v_pk_add_f32 v[134:135], v[138:139], v[134:135]
	v_mov_b32_e32 v136, v132
	v_mov_b32_e32 v137, v130
	v_mov_b32_e32 v130, v133
	v_pk_add_f32 v[130:131], v[136:137], v[130:131]
	v_add_f32_e32 v0, v134, v135
	v_add_f32_e32 v0, v0, v131
	v_add_f32_e32 v0, v130, v0
	v_fmamk_f32 v0, v0, 0x3a800000, v201
	v_cmp_gt_f32_e32 vcc, s6, v0
	v_mul_f32_e32 v130, 0x4b800000, v0
	s_lshl_b32 s6, s54, 6
	v_cndmask_b32_e32 v0, v0, v130, vcc
	v_rsq_f32_e32 v0, v0
	s_or_b32 s11, s6, s86
	s_mul_i32 s6, s50, 0xfffffe84
	s_add_u32 s6, s64, s6
	v_mul_f32_e32 v130, 0x45800000, v0
	v_cndmask_b32_e32 v0, v0, v130, vcc
	v_lshl_add_u32 v130, v145, 2, 0
	v_add_u32_e32 v130, 0x12000, v130
	s_addc_u32 s7, s65, s96
	ds_write_b32 v130, v0
	s_waitcnt lgkmcnt(0)
	s_barrier
	s_load_dword s31, s[6:7], 0x998
	s_mov_b64 s[6:7], 0
	s_waitcnt lgkmcnt(0)
	s_cmp_gt_i32 s31, 1
	s_cselect_b64 s[94:95], -1, 0
	s_cmp_lt_i32 s31, 2
	s_cbranch_scc1 .LBB0_121
	s_cmp_eq_u32 s31, 2
	s_cbranch_scc1 .LBB0_117
	s_add_i32 s8, s31, -1
	s_and_b32 s9, s8, -2
	s_mov_b32 s33, s11
	s_mov_b32 s6, 2
	s_mov_b32 s58, 1
	s_brev_b32 s36, 1
	s_mov_b32 s38, s9
	s_brev_b32 s37, 1
